# stack: + attention row-max lane^32 exchange via v_permlane32_swap instead of ds_bpermute (compressed and selected branches)
# speedup vs baseline: 1.0055x; 1.0025x over previous
.LBB0_223:
	s_mul_i32 s20, s18, 0x4800
	s_add_i32 s20, s20, 0
	s_lshl_b32 s26, s26, 6
	v_add_u32_e32 v0, s20, v170
	v_add_u32_e32 v193, s20, v171
	s_cmp_gt_i32 s26, s19
	v_add_u32_e32 v211, v0, v204
	s_cbranch_scc1 .LBB0_231
	s_lshl_b32 s94, s26, 1
	v_lshl_add_u64 v[66:67], v[180:181], 0, s[94:95]
	global_load_dwordx4 v[146:149], v[66:67], off
	global_load_dwordx4 v[142:145], v[66:67], off offset:32
	v_add_co_u32_e32 v66, vcc, 0x4000, v66
	s_or_b32 s20, s26, 31
	s_nop 0
	v_addc_co_u32_e32 v67, vcc, 0, v67, vcc
	global_load_dwordx4 v[150:153], v[66:67], off
	global_load_dwordx4 v[138:141], v[66:67], off offset:32
	ds_read_b128 v[66:69], v211
	ds_read_b128 v[212:215], v211 offset:32
	s_cmp_le_i32 s20, s24
	s_mov_b64 s[20:21], -1
	s_waitcnt lgkmcnt(0)
	v_mfma_f32_32x32x16_bf16 v[66:81], v[66:69], v[110:113], 0
	v_mfma_f32_32x32x16_bf16 v[66:81], v[212:215], v[82:85], v[66:81]
	ds_read_b128 v[212:215], v211 offset:64
	s_waitcnt lgkmcnt(0)
	v_mfma_f32_32x32x16_bf16 v[66:81], v[212:215], v[114:117], v[66:81]
	ds_read_b128 v[212:215], v211 offset:96
	s_waitcnt lgkmcnt(0)
	v_mfma_f32_32x32x16_bf16 v[66:81], v[212:215], v[86:89], v[66:81]
	s_cbranch_scc0 .LBB0_240
	s_nop 10
	v_max3_f32 v0, v66, s72, v67
	v_max3_f32 v0, v0, v68, v69
	v_max3_f32 v0, v0, v70, v71
	v_max3_f32 v0, v0, v72, v73
	v_max3_f32 v0, v0, v74, v75
	v_max3_f32 v0, v0, v76, v77
	v_max3_f32 v0, v0, v78, v79
	v_max3_f32 v0, v0, v80, v81
	v_mul_f32_e32 v0, 0x3e38aa3b, v0
	v_cndmask_b32_e64 v0, v230, v0, s[8:9]
	v_mov_b32_e32 v210, v0
	v_mov_b32_e32 v226, v0
	s_nop 1
	v_permlane32_swap_b32_e32 v210, v226
	v_max_f32_e32 v226, v210, v226
	s_waitcnt lgkmcnt(0)
	v_max3_f32 v210, v209, v0, v226
	v_fma_f32 v0, v66, s36, -v210
	v_exp_f32_e32 v213, v0
	v_fma_f32 v0, v67, s36, -v210
	v_exp_f32_e32 v212, v0
	v_fma_f32 v0, v68, s36, -v210
	v_exp_f32_e32 v215, v0
	v_fma_f32 v0, v69, s36, -v210
	v_exp_f32_e32 v214, v0
	v_fma_f32 v216, v70, s36, -v210
	v_add_f32_e32 v0, 0, v213
	v_exp_f32_e32 v217, v216
	v_fma_f32 v216, v71, s36, -v210
	v_add_f32_e32 v0, v212, v0
	v_exp_f32_e32 v216, v216
	v_fma_f32 v220, v72, s36, -v210
	v_add_f32_e32 v0, v215, v0
	v_exp_f32_e32 v239, v220
	v_fma_f32 v220, v73, s36, -v210
	v_add_f32_e32 v0, v214, v0
	v_exp_f32_e32 v238, v220
	v_fma_f32 v220, v74, s36, -v210
	v_add_f32_e32 v0, v217, v0
	v_exp_f32_e32 v241, v220
	v_fma_f32 v220, v75, s36, -v210
	v_add_f32_e32 v0, v216, v0
	v_exp_f32_e32 v240, v220
	v_fma_f32 v220, v76, s36, -v210
	v_add_f32_e32 v0, v239, v0
	v_exp_f32_e32 v244, v220
	v_fma_f32 v220, v77, s36, -v210
	v_add_f32_e32 v0, v238, v0
	v_exp_f32_e32 v243, v220
	v_fma_f32 v220, v78, s36, -v210
	v_add_f32_e32 v0, v241, v0
	v_exp_f32_e32 v246, v220
	v_fma_f32 v220, v79, s36, -v210
	v_add_f32_e32 v0, v240, v0
	v_exp_f32_e32 v245, v220
	v_fma_f32 v220, v80, s36, -v210
	v_add_f32_e32 v0, v244, v0
	v_exp_f32_e32 v248, v220
	v_fma_f32 v220, v81, s36, -v210
	v_add_f32_e32 v0, v243, v0
	v_exp_f32_e32 v247, v220
	v_add_f32_e32 v0, v246, v0
	v_add_f32_e32 v0, v245, v0
	v_add_f32_e32 v0, v248, v0
	v_add_f32_e32 v242, v247, v0
	s_and_saveexec_b64 s[20:21], s[10:11]
	s_cbranch_execz .LBB0_227
	v_mov_b32_e32 v247, 0
	v_mov_b32_e32 v248, 0
	v_mov_b32_e32 v245, 0
	v_mov_b32_e32 v246, 0
	v_mov_b32_e32 v243, 0
	v_mov_b32_e32 v244, 0
	v_mov_b32_e32 v240, 0
	v_mov_b32_e32 v241, 0
	v_mov_b32_e32 v238, 0
	v_mov_b32_e32 v239, 0
	v_mov_b32_e32 v216, 0
	v_mov_b32_e32 v217, 0
	v_mov_b32_e32 v214, 0
	v_mov_b32_e32 v215, 0
	v_mov_b32_e32 v212, 0
	v_mov_b32_e32 v213, 0
	v_mov_b32_e32 v242, 0

.LBB0_232:
	s_lshl_b32 s94, s26, 1
	v_lshl_add_u64 v[66:67], v[180:181], 0, s[94:95]
	global_load_dwordx4 v[146:149], v[66:67], off offset:64
	global_load_dwordx4 v[142:145], v[66:67], off offset:96
	v_add_co_u32_e32 v66, vcc, 0x4000, v66
	s_or_b32 s20, s26, 63
	s_nop 0
	v_addc_co_u32_e32 v67, vcc, 0, v67, vcc
	global_load_dwordx4 v[150:153], v[66:67], off offset:64
	global_load_dwordx4 v[138:141], v[66:67], off offset:96
	ds_read_b128 v[66:69], v211 offset:4608
	ds_read_b128 v[212:215], v211 offset:4640
	s_waitcnt lgkmcnt(0)
	v_mfma_f32_32x32x16_bf16 v[66:81], v[66:69], v[110:113], 0
	s_cmp_gt_i32 s20, s24
	s_mov_b64 s[20:21], -1
	v_mfma_f32_32x32x16_bf16 v[66:81], v[212:215], v[82:85], v[66:81]
	ds_read_b128 v[212:215], v211 offset:4672
	s_waitcnt lgkmcnt(0)
	v_mfma_f32_32x32x16_bf16 v[66:81], v[212:215], v[114:117], v[66:81]
	ds_read_b128 v[212:215], v211 offset:4704
	s_waitcnt lgkmcnt(0)
	v_mfma_f32_32x32x16_bf16 v[66:81], v[212:215], v[86:89], v[66:81]
	s_cbranch_scc1 .LBB0_242
	s_nop 10
	v_max3_f32 v0, v66, s72, v67
	v_max3_f32 v0, v0, v68, v69
	v_max3_f32 v0, v0, v70, v71
	v_max3_f32 v0, v0, v72, v73
	v_max3_f32 v0, v0, v74, v75
	v_max3_f32 v0, v0, v76, v77
	v_max3_f32 v0, v0, v78, v79
	v_max3_f32 v0, v0, v80, v81
	v_mul_f32_e32 v0, 0x3e38aa3b, v0
	v_cndmask_b32_e64 v0, v230, v0, s[8:9]
	v_mov_b32_e32 v209, v0
	v_mov_b32_e32 v226, v0
	s_nop 1
	v_permlane32_swap_b32_e32 v209, v226
	v_max_f32_e32 v226, v209, v226
	s_waitcnt lgkmcnt(0)
	v_max3_f32 v209, v210, v0, v226
	v_fma_f32 v0, v66, s36, -v209
	v_exp_f32_e32 v212, v0
	v_fma_f32 v0, v67, s36, -v209
	v_exp_f32_e32 v211, v0
	v_fma_f32 v0, v68, s36, -v209
	v_exp_f32_e32 v214, v0
	v_fma_f32 v0, v69, s36, -v209
	v_exp_f32_e32 v213, v0
	v_fma_f32 v215, v70, s36, -v209
	v_add_f32_e32 v0, 0, v212
	v_exp_f32_e32 v216, v215
	v_fma_f32 v215, v71, s36, -v209
	v_add_f32_e32 v0, v211, v0
	v_exp_f32_e32 v215, v215
	v_fma_f32 v217, v72, s36, -v209
	v_add_f32_e32 v0, v214, v0
	v_exp_f32_e32 v238, v217
	v_fma_f32 v217, v73, s36, -v209
	v_add_f32_e32 v0, v213, v0
	v_exp_f32_e32 v217, v217
	v_fma_f32 v220, v74, s36, -v209
	v_add_f32_e32 v0, v216, v0
	v_exp_f32_e32 v240, v220
	v_fma_f32 v220, v75, s36, -v209
	v_add_f32_e32 v0, v215, v0
	v_exp_f32_e32 v239, v220
	v_fma_f32 v220, v76, s36, -v209
	v_add_f32_e32 v0, v238, v0
	v_exp_f32_e32 v243, v220
	v_fma_f32 v220, v77, s36, -v209
	v_add_f32_e32 v0, v217, v0
	v_exp_f32_e32 v242, v220
	v_fma_f32 v220, v78, s36, -v209
	v_add_f32_e32 v0, v240, v0
	v_exp_f32_e32 v245, v220
	v_fma_f32 v220, v79, s36, -v209
	v_add_f32_e32 v0, v239, v0
	v_exp_f32_e32 v244, v220
	v_fma_f32 v220, v80, s36, -v209
	v_add_f32_e32 v0, v243, v0
	v_exp_f32_e32 v247, v220
	v_fma_f32 v220, v81, s36, -v209
	v_add_f32_e32 v0, v242, v0
	v_exp_f32_e32 v246, v220
	v_add_f32_e32 v0, v245, v0
	v_add_f32_e32 v0, v244, v0
	v_add_f32_e32 v0, v247, v0
	v_add_f32_e32 v241, v246, v0
	s_and_saveexec_b64 s[20:21], s[10:11]
	s_cbranch_execz .LBB0_235
	v_mov_b32_e32 v246, 0
	v_mov_b32_e32 v247, 0
	v_mov_b32_e32 v244, 0
	v_mov_b32_e32 v245, 0
	v_mov_b32_e32 v242, 0
	v_mov_b32_e32 v243, 0
	v_mov_b32_e32 v239, 0
	v_mov_b32_e32 v240, 0
	v_mov_b32_e32 v217, 0
	v_mov_b32_e32 v238, 0
	v_mov_b32_e32 v215, 0
	v_mov_b32_e32 v216, 0
	v_mov_b32_e32 v213, 0
	v_mov_b32_e32 v214, 0
	v_mov_b32_e32 v211, 0
	v_mov_b32_e32 v212, 0
	v_mov_b32_e32 v241, 0

.LBB0_351:
	v_lshrrev_b64 v[66:67], s24, v[110:111]
	v_and_b32_e32 v0, 1, v66
	v_cmp_eq_u32_e32 vcc, 1, v0
	s_mul_i32 s8, s19, 0x4800
	s_add_i32 s25, s8, 0
	v_cndmask_b32_e32 v88, -1, v192, vcc
	v_cmp_lt_i32_e64 s[10:11], -1, v88
	s_cmp_eq_u64 s[10:11], 0
	s_cselect_b64 s[20:21], -1, 0
	s_lshl_b32 s27, s24, 6
	s_cmp_gt_i32 s27, s61
	v_add_u32_e32 v0, s25, v170
	v_add_u32_e32 v86, s25, v171
	s_cselect_b64 s[24:25], -1, 0
	s_or_b64 s[24:25], s[20:21], s[24:25]
	v_cmp_gt_i32_e64 s[8:9], 0, v88
	s_and_b64 vcc, exec, s[24:25]
	v_add_u32_e32 v90, v0, v204
	s_cbranch_vccnz .LBB0_359
	ds_read_b128 v[66:69], v90
	ds_read_b128 v[92:95], v90 offset:32
	s_or_b32 s24, s27, 31
	s_cmp_le_i32 s24, s91
	s_mov_b64 s[24:25], -1
	s_waitcnt lgkmcnt(0)
	v_mfma_f32_32x32x16_bf16 v[66:81], v[66:69], v[114:117], 0
	v_mfma_f32_32x32x16_bf16 v[66:81], v[92:95], v[118:121], v[66:81]
	ds_read_b128 v[92:95], v90 offset:64
	s_waitcnt lgkmcnt(0)
	v_mfma_f32_32x32x16_bf16 v[66:81], v[92:95], v[126:129], v[66:81]
	ds_read_b128 v[92:95], v90 offset:96
	s_waitcnt lgkmcnt(0)
	v_mfma_f32_32x32x16_bf16 v[66:81], v[92:95], v[122:125], v[66:81]
	s_cbranch_scc0 .LBB0_369
	s_nop 10
	v_max3_f32 v0, v66, s72, v67
	v_max3_f32 v0, v0, v68, v69
	v_max3_f32 v0, v0, v70, v71
	v_max3_f32 v0, v0, v72, v73
	v_max3_f32 v0, v0, v74, v75
	v_max3_f32 v0, v0, v76, v77
	v_max3_f32 v0, v0, v78, v79
	v_max3_f32 v0, v0, v80, v81
	v_mul_f32_e32 v0, 0x3e38aa3b, v0
	v_cndmask_b32_e64 v0, v230, v0, s[10:11]
	v_mov_b32_e32 v89, v0
	v_mov_b32_e32 v226, v0
	s_nop 1
	v_permlane32_swap_b32_e32 v89, v226
	v_max_f32_e32 v226, v89, v226
	s_waitcnt lgkmcnt(0)
	v_max3_f32 v89, v87, v0, v226
	v_cndmask_b32_e64 v221, -v230, v89, s[10:11]
	v_fma_f32 v0, v66, s36, -v221
	v_exp_f32_e32 v91, v0
	v_fma_f32 v0, v67, s36, -v221
	v_exp_f32_e32 v92, v0
	v_fma_f32 v0, v68, s36, -v221
	v_exp_f32_e32 v95, v0
	v_fma_f32 v0, v69, s36, -v221
	v_exp_f32_e32 v94, v0
	v_fma_f32 v93, v70, s36, -v221
	v_add_f32_e32 v0, 0, v91
	v_exp_f32_e32 v97, v93
	v_fma_f32 v93, v71, s36, -v221
	v_add_f32_e32 v0, v92, v0
	v_exp_f32_e32 v96, v93
	v_fma_f32 v93, v72, s36, -v221
	v_add_f32_e32 v0, v95, v0
	v_exp_f32_e32 v99, v93
	v_fma_f32 v93, v73, s36, -v221
	v_add_f32_e32 v0, v94, v0
	v_exp_f32_e32 v98, v93
	v_fma_f32 v93, v74, s36, -v221
	v_add_f32_e32 v0, v97, v0
	v_exp_f32_e32 v101, v93
	v_fma_f32 v93, v75, s36, -v221
	v_add_f32_e32 v0, v96, v0
	v_exp_f32_e32 v100, v93
	v_fma_f32 v93, v76, s36, -v221
	v_add_f32_e32 v0, v99, v0
	v_exp_f32_e32 v103, v93
	v_fma_f32 v93, v77, s36, -v221
	v_add_f32_e32 v0, v98, v0
	v_exp_f32_e32 v102, v93
	v_fma_f32 v93, v78, s36, -v221
	v_add_f32_e32 v0, v101, v0
	v_exp_f32_e32 v105, v93
	v_fma_f32 v93, v79, s36, -v221
	v_add_f32_e32 v0, v100, v0
	v_exp_f32_e32 v104, v93
	v_fma_f32 v93, v80, s36, -v221
	v_add_f32_e32 v0, v103, v0
	v_exp_f32_e32 v107, v93
	v_fma_f32 v93, v81, s36, -v221
	v_add_f32_e32 v0, v102, v0
	v_exp_f32_e32 v106, v93
	v_add_f32_e32 v0, v105, v0
	v_add_f32_e32 v0, v104, v0
	v_add_f32_e32 v0, v107, v0
	v_add_f32_e32 v93, v106, v0
	v_sub_f32_e32 v0, v87, v89
	v_exp_f32_e32 v0, v0
	s_cbranch_execz .LBB0_370

.LBB0_360:
	s_or_b32 s24, s27, 32
	s_cmp_gt_i32 s24, s61
	s_cselect_b64 s[28:29], -1, 0
	s_or_b64 s[20:21], s[20:21], s[28:29]
	s_and_b64 vcc, exec, s[20:21]
	s_cbranch_vccnz .LBB0_346
	ds_read_b128 v[66:69], v90 offset:4608
	ds_read_b128 v[92:95], v90 offset:4640
	s_or_b32 s20, s27, 63
	s_cmp_gt_i32 s20, s91
	s_mov_b64 s[20:21], -1
	s_waitcnt lgkmcnt(0)
	v_mfma_f32_32x32x16_bf16 v[66:81], v[66:69], v[114:117], 0
	v_mfma_f32_32x32x16_bf16 v[66:81], v[92:95], v[118:121], v[66:81]
	ds_read_b128 v[92:95], v90 offset:4672
	s_waitcnt lgkmcnt(0)
	v_mfma_f32_32x32x16_bf16 v[66:81], v[92:95], v[126:129], v[66:81]
	ds_read_b128 v[90:93], v90 offset:4704
	s_waitcnt lgkmcnt(0)
	v_mfma_f32_32x32x16_bf16 v[66:81], v[90:93], v[122:125], v[66:81]
	s_cbranch_scc1 .LBB0_371
	s_nop 10
	v_max3_f32 v0, v66, s72, v67
	v_max3_f32 v0, v0, v68, v69
	v_max3_f32 v0, v0, v70, v71
	v_max3_f32 v0, v0, v72, v73
	v_max3_f32 v0, v0, v74, v75
	v_max3_f32 v0, v0, v76, v77
	v_max3_f32 v0, v0, v78, v79
	v_max3_f32 v0, v0, v80, v81
	v_mul_f32_e32 v0, 0x3e38aa3b, v0
	v_cndmask_b32_e64 v0, v230, v0, s[10:11]
	v_mov_b32_e32 v87, v0
	v_mov_b32_e32 v226, v0
	s_nop 1
	v_permlane32_swap_b32_e32 v87, v226
	v_max_f32_e32 v226, v87, v226
	s_waitcnt lgkmcnt(0)
	v_max3_f32 v87, v89, v0, v226
	v_cndmask_b32_e64 v221, -v230, v87, s[10:11]
	v_fma_f32 v0, v66, s36, -v221
	v_exp_f32_e32 v90, v0
	v_fma_f32 v0, v67, s36, -v221
	v_exp_f32_e32 v91, v0
	v_fma_f32 v0, v68, s36, -v221
	v_exp_f32_e32 v94, v0
	v_fma_f32 v0, v69, s36, -v221
	v_exp_f32_e32 v93, v0
	v_fma_f32 v92, v70, s36, -v221
	v_add_f32_e32 v0, 0, v90
	v_exp_f32_e32 v96, v92
	v_fma_f32 v92, v71, s36, -v221
	v_add_f32_e32 v0, v91, v0
	v_exp_f32_e32 v95, v92
	v_fma_f32 v92, v72, s36, -v221
	v_add_f32_e32 v0, v94, v0
	v_exp_f32_e32 v98, v92
	v_fma_f32 v92, v73, s36, -v221
	v_add_f32_e32 v0, v93, v0
	v_exp_f32_e32 v97, v92
	v_fma_f32 v92, v74, s36, -v221
	v_add_f32_e32 v0, v96, v0
	v_exp_f32_e32 v100, v92
	v_fma_f32 v92, v75, s36, -v221
	v_add_f32_e32 v0, v95, v0
	v_exp_f32_e32 v99, v92
	v_fma_f32 v92, v76, s36, -v221
	v_add_f32_e32 v0, v98, v0
	v_exp_f32_e32 v102, v92
	v_fma_f32 v92, v77, s36, -v221
	v_add_f32_e32 v0, v97, v0
	v_exp_f32_e32 v101, v92
	v_fma_f32 v92, v78, s36, -v221
	v_add_f32_e32 v0, v100, v0
	v_exp_f32_e32 v104, v92
	v_fma_f32 v92, v79, s36, -v221
	v_add_f32_e32 v0, v99, v0
	v_exp_f32_e32 v103, v92
	v_fma_f32 v92, v80, s36, -v221
	v_add_f32_e32 v0, v102, v0
	v_exp_f32_e32 v106, v92
	v_fma_f32 v92, v81, s36, -v221
	v_add_f32_e32 v0, v101, v0
	v_exp_f32_e32 v105, v92
	v_add_f32_e32 v0, v104, v0
	v_add_f32_e32 v0, v103, v0
	v_add_f32_e32 v0, v106, v0
	v_add_f32_e32 v92, v105, v0
	v_sub_f32_e32 v0, v89, v87
	v_exp_f32_e32 v0, v0
	s_cbranch_execz .LBB0_372
